# NSA interior tiles: cross-half row max via v_permlane32_swap instead of ds_bpermute + lgkmcnt(0)
# baseline (speedup 1.0000x reference)
.LBB0_283:
	s_add_i32 s13, s12, 1
	s_min_i32 s4, s13, s10
	s_lshl_b32 s96, s4, 6
	v_add_u32_e32 v2, s96, v158
	v_add_u32_e32 v4, s96, v160
	v_ashrrev_i32_e32 v3, 31, v2
	v_ashrrev_i32_e32 v5, 31, v4
	v_lshlrev_b64 v[2:3], 7, v[2:3]
	v_lshlrev_b64 v[4:5], 7, v[4:5]
	v_lshl_add_u64 v[2:3], v[170:171], 0, v[2:3]
	v_lshl_add_u64 v[4:5], v[170:171], 0, v[4:5]
	s_lshl_b64 s[4:5], s[96:97], 1
	global_load_dwordx4 v[8:11], v[2:3], off
	s_nop 0
	global_load_dwordx4 v[4:7], v[4:5], off
	v_lshl_add_u64 v[2:3], v[162:163], 0, s[4:5]
	v_lshl_add_u64 v[48:49], v[164:165], 0, s[4:5]
	global_load_dwordx4 v[12:15], v[2:3], off
	global_load_dwordx4 v[112:115], v[48:49], off
	s_and_b32 s14, s12, 1
	s_mul_i32 s4, s14, 0x4800
	v_lshrrev_b64 v[2:3], s12, v[128:129]
	s_lshl_b32 s15, s12, 6
	v_and_b32_e32 v0, 1, v2
	s_or_b32 s5, s15, 63
	v_or_b32_e32 v3, s4, v131
	v_cmp_eq_u64_e64 s[38:39], 0, v[0:1]
	s_cmp_gt_i32 s5, s8
	v_add_u32_e32 v172, v3, v161
	s_mov_b64 s[4:5], -1
	s_cbranch_scc1 .LBB0_289
	v_mad_u32_u24 v0, v116, s37, v3
	v_lshl_add_u32 v215, v156, 1, v172
	ds_read_b128 v[220:223], v0
	ds_read_b128 v[236:239], v0 offset:4608
	ds_read_b128 v[224:227], v0 offset:32
	ds_read_b128 v[240:243], v0 offset:4640
	ds_read_b128 v[228:231], v0 offset:64
	ds_read_b128 v[244:247], v0 offset:4672
	ds_read_b128 v[232:235], v0 offset:96
	ds_read_b128 v[248:251], v0 offset:4704
	v_add_u32_e32 v214, 0x3000, v215
	v_add_u32_e32 v215, 0x2000, v215
	ds_read2_b64 v[64:67], v215 offset0:128 offset1:130
	ds_read2_b64 v[68:71], v214 offset0:192 offset1:194
	ds_read2_b64 v[72:75], v215 offset0:132 offset1:134
	ds_read2_b64 v[76:79], v214 offset0:196 offset1:198
	s_waitcnt lgkmcnt(11)
	v_mfma_f32_32x32x16_bf16 v[80:95], v[220:223], v[96:99], 0
	s_waitcnt lgkmcnt(10)
	v_mfma_f32_32x32x16_bf16 v[48:63], v[236:239], v[96:99], 0
	s_waitcnt lgkmcnt(9)
	v_mfma_f32_32x32x16_bf16 v[80:95], v[224:227], v[100:103], v[80:95]
	s_waitcnt lgkmcnt(8)
	v_mfma_f32_32x32x16_bf16 v[48:63], v[240:243], v[100:103], v[48:63]
	s_waitcnt lgkmcnt(7)
	v_mfma_f32_32x32x16_bf16 v[80:95], v[228:231], v[104:107], v[80:95]
	s_waitcnt lgkmcnt(6)
	v_mfma_f32_32x32x16_bf16 v[48:63], v[244:247], v[104:107], v[48:63]
	s_waitcnt lgkmcnt(5)
	v_mfma_f32_32x32x16_bf16 v[80:95], v[232:235], v[108:111], v[80:95]
	s_waitcnt lgkmcnt(4)
	v_mfma_f32_32x32x16_bf16 v[48:63], v[248:251], v[108:111], v[48:63]
	ds_read2_b64 v[220:223], v215 offset0:136 offset1:138
	ds_read2_b64 v[224:227], v214 offset0:200 offset1:202
	ds_read2_b64 v[228:231], v215 offset0:140 offset1:142
	ds_read2_b64 v[232:235], v214 offset0:204 offset1:206
	s_nop 7
	v_max3_f32 v0, v80, v81, v82
	v_max3_f32 v2, v88, v89, v90
	v_max3_f32 v0, v0, v83, v84
	v_max3_f32 v2, v2, v91, v92
	v_max3_f32 v0, v0, v85, v86
	v_max3_f32 v2, v2, v93, v94
	v_max3_f32 v0, v0, v87, v95
	v_max_f32_e32 v0, v0, v2
	v_cndmask_b32_e64 v0, v0, v202, s[38:39]
	v_mov_b32_e32 v2, v0
	s_nop 1
	v_permlane32_swap_b32_e32 v0, v2
	v_max3_f32 v173, v167, v0, v2
	v_sub_f32_e32 v0, v167, v173
	v_exp_f32_e32 v0, v0
	v_cmp_eq_f32_e32 vcc, v173, v167
	s_cmp_eq_u64 vcc, exec
	s_cbranch_scc1 .Lnsw_keep0
	v_pk_mul_f32 v[46:47], v[46:47], v[0:1] op_sel_hi:[1,0]
	v_pk_mul_f32 v[44:45], v[44:45], v[0:1] op_sel_hi:[1,0]
	v_pk_mul_f32 v[42:43], v[42:43], v[0:1] op_sel_hi:[1,0]
	v_pk_mul_f32 v[40:41], v[40:41], v[0:1] op_sel_hi:[1,0]
	v_pk_mul_f32 v[38:39], v[38:39], v[0:1] op_sel_hi:[1,0]
	v_pk_mul_f32 v[36:37], v[36:37], v[0:1] op_sel_hi:[1,0]
	v_pk_mul_f32 v[34:35], v[34:35], v[0:1] op_sel_hi:[1,0]
	v_pk_mul_f32 v[32:33], v[32:33], v[0:1] op_sel_hi:[1,0]
	v_pk_mul_f32 v[30:31], v[30:31], v[0:1] op_sel_hi:[1,0]
	v_pk_mul_f32 v[28:29], v[28:29], v[0:1] op_sel_hi:[1,0]
	v_pk_mul_f32 v[26:27], v[26:27], v[0:1] op_sel_hi:[1,0]
	v_pk_mul_f32 v[24:25], v[24:25], v[0:1] op_sel_hi:[1,0]
	v_pk_mul_f32 v[22:23], v[22:23], v[0:1] op_sel_hi:[1,0]
	v_pk_mul_f32 v[20:21], v[20:21], v[0:1] op_sel_hi:[1,0]
	v_pk_mul_f32 v[18:19], v[18:19], v[0:1] op_sel_hi:[1,0]
	v_pk_mul_f32 v[16:17], v[16:17], v[0:1] op_sel_hi:[1,0]
.Lnsw_keep0:
	v_mov_b32_e32 v167, v173
	v_cndmask_b32_e64 v174, v173, v206, s[38:39]
	v_sub_f32_e32 v80, v80, v174
	v_exp_f32_e32 v80, v80
	v_sub_f32_e32 v81, v81, v174
	v_exp_f32_e32 v81, v81
	v_add_f32_e32 v213, 0, v80
	v_sub_f32_e32 v82, v82, v174
	v_exp_f32_e32 v82, v82
	v_add_f32_e32 v213, v81, v213
	v_sub_f32_e32 v83, v83, v174
	v_exp_f32_e32 v83, v83
	v_add_f32_e32 v213, v82, v213
	v_cvt_pk_bf16_f32 v176, v80, v81
	v_sub_f32_e32 v84, v84, v174
	v_exp_f32_e32 v84, v84
	v_add_f32_e32 v213, v83, v213
	v_sub_f32_e32 v85, v85, v174
	v_exp_f32_e32 v85, v85
	v_add_f32_e32 v213, v84, v213
	v_cvt_pk_bf16_f32 v177, v82, v83
	v_sub_f32_e32 v86, v86, v174
	v_exp_f32_e32 v86, v86
	v_add_f32_e32 v213, v85, v213
	v_sub_f32_e32 v87, v87, v174
	v_exp_f32_e32 v87, v87
	v_add_f32_e32 v213, v86, v213
	v_cvt_pk_bf16_f32 v178, v84, v85
	v_sub_f32_e32 v88, v88, v174
	v_exp_f32_e32 v88, v88
	v_add_f32_e32 v213, v87, v213
	v_sub_f32_e32 v89, v89, v174
	v_exp_f32_e32 v89, v89
	v_add_f32_e32 v213, v88, v213
	v_cvt_pk_bf16_f32 v179, v86, v87
	v_sub_f32_e32 v90, v90, v174
	v_exp_f32_e32 v90, v90
	v_add_f32_e32 v213, v89, v213
	s_waitcnt lgkmcnt(7)
	v_mfma_f32_32x32x16_bf16 v[32:47], v[64:67], v[176:179], v[32:47]
	s_waitcnt lgkmcnt(6)
	v_mfma_f32_32x32x16_bf16 v[16:31], v[68:71], v[176:179], v[16:31]
	v_sub_f32_e32 v91, v91, v174
	v_exp_f32_e32 v91, v91
	v_add_f32_e32 v213, v90, v213
	v_cvt_pk_bf16_f32 v180, v88, v89
	v_sub_f32_e32 v92, v92, v174
	v_exp_f32_e32 v92, v92
	v_add_f32_e32 v213, v91, v213
	v_sub_f32_e32 v93, v93, v174
	v_exp_f32_e32 v93, v93
	v_add_f32_e32 v213, v92, v213
	v_cvt_pk_bf16_f32 v181, v90, v91
	v_sub_f32_e32 v94, v94, v174
	v_exp_f32_e32 v94, v94
	v_add_f32_e32 v213, v93, v213
	v_sub_f32_e32 v95, v95, v174
	v_exp_f32_e32 v95, v95
	v_add_f32_e32 v213, v94, v213
	v_cvt_pk_bf16_f32 v182, v92, v93
	v_add_f32_e32 v213, v95, v213
	v_cvt_pk_bf16_f32 v183, v94, v95
	v_fmac_f32_e32 v213, v169, v0
	v_mov_b32_e32 v169, v213
	s_nop 0
	s_waitcnt lgkmcnt(5)
	v_mfma_f32_32x32x16_bf16 v[32:47], v[72:75], v[180:183], v[32:47]
	s_waitcnt lgkmcnt(4)
	v_mfma_f32_32x32x16_bf16 v[16:31], v[76:79], v[180:183], v[16:31]
	v_max3_f32 v0, v48, v49, v50
	v_max3_f32 v2, v56, v57, v58
	v_max3_f32 v0, v0, v51, v52
	v_max3_f32 v2, v2, v59, v60
	v_max3_f32 v0, v0, v53, v54
	v_max3_f32 v2, v2, v61, v62
	v_max3_f32 v0, v0, v55, v63
	v_max_f32_e32 v0, v0, v2
	v_cndmask_b32_e64 v0, v0, v202, s[38:39]
	v_mov_b32_e32 v2, v0
	s_nop 1
	v_permlane32_swap_b32_e32 v0, v2
	v_max3_f32 v173, v167, v0, v2
	v_sub_f32_e32 v0, v167, v173
	v_exp_f32_e32 v0, v0
	v_cmp_eq_f32_e32 vcc, v173, v167
	s_cmp_eq_u64 vcc, exec
	s_cbranch_scc1 .Lnsw_keep1
	v_pk_mul_f32 v[46:47], v[46:47], v[0:1] op_sel_hi:[1,0]
	v_pk_mul_f32 v[44:45], v[44:45], v[0:1] op_sel_hi:[1,0]
	v_pk_mul_f32 v[42:43], v[42:43], v[0:1] op_sel_hi:[1,0]
	v_pk_mul_f32 v[40:41], v[40:41], v[0:1] op_sel_hi:[1,0]
	v_pk_mul_f32 v[38:39], v[38:39], v[0:1] op_sel_hi:[1,0]
	v_pk_mul_f32 v[36:37], v[36:37], v[0:1] op_sel_hi:[1,0]
	v_pk_mul_f32 v[34:35], v[34:35], v[0:1] op_sel_hi:[1,0]
	v_pk_mul_f32 v[32:33], v[32:33], v[0:1] op_sel_hi:[1,0]
	v_pk_mul_f32 v[30:31], v[30:31], v[0:1] op_sel_hi:[1,0]
	v_pk_mul_f32 v[28:29], v[28:29], v[0:1] op_sel_hi:[1,0]
	v_pk_mul_f32 v[26:27], v[26:27], v[0:1] op_sel_hi:[1,0]
	v_pk_mul_f32 v[24:25], v[24:25], v[0:1] op_sel_hi:[1,0]
	v_pk_mul_f32 v[22:23], v[22:23], v[0:1] op_sel_hi:[1,0]
	v_pk_mul_f32 v[20:21], v[20:21], v[0:1] op_sel_hi:[1,0]
	v_pk_mul_f32 v[18:19], v[18:19], v[0:1] op_sel_hi:[1,0]
	v_pk_mul_f32 v[16:17], v[16:17], v[0:1] op_sel_hi:[1,0]
.Lnsw_keep1:
	v_mov_b32_e32 v167, v173
	v_cndmask_b32_e64 v174, v173, v206, s[38:39]
	v_sub_f32_e32 v48, v48, v174
	v_exp_f32_e32 v48, v48
	v_sub_f32_e32 v49, v49, v174
	v_exp_f32_e32 v49, v49
	v_add_f32_e32 v213, 0, v48
	v_sub_f32_e32 v50, v50, v174
	v_exp_f32_e32 v50, v50
	v_add_f32_e32 v213, v49, v213
	v_sub_f32_e32 v51, v51, v174
	v_exp_f32_e32 v51, v51
	v_add_f32_e32 v213, v50, v213
	v_cvt_pk_bf16_f32 v80, v48, v49
	v_sub_f32_e32 v52, v52, v174
	v_exp_f32_e32 v52, v52
	v_add_f32_e32 v213, v51, v213
	v_sub_f32_e32 v53, v53, v174
	v_exp_f32_e32 v53, v53
	v_add_f32_e32 v213, v52, v213
	v_cvt_pk_bf16_f32 v81, v50, v51
	v_sub_f32_e32 v54, v54, v174
	v_exp_f32_e32 v54, v54
	v_add_f32_e32 v213, v53, v213
	v_sub_f32_e32 v55, v55, v174
	v_exp_f32_e32 v55, v55
	v_add_f32_e32 v213, v54, v213
	v_cvt_pk_bf16_f32 v82, v52, v53
	v_sub_f32_e32 v56, v56, v174
	v_exp_f32_e32 v56, v56
	v_add_f32_e32 v213, v55, v213
	v_sub_f32_e32 v57, v57, v174
	v_exp_f32_e32 v57, v57
	v_add_f32_e32 v213, v56, v213
	v_cvt_pk_bf16_f32 v83, v54, v55
	v_sub_f32_e32 v58, v58, v174
	v_exp_f32_e32 v58, v58
	v_add_f32_e32 v213, v57, v213
	s_waitcnt lgkmcnt(3)
	v_mfma_f32_32x32x16_bf16 v[32:47], v[220:223], v[80:83], v[32:47]
	s_waitcnt lgkmcnt(2)
	v_mfma_f32_32x32x16_bf16 v[16:31], v[224:227], v[80:83], v[16:31]
	v_sub_f32_e32 v59, v59, v174
	v_exp_f32_e32 v59, v59
	v_add_f32_e32 v213, v58, v213
	v_cvt_pk_bf16_f32 v84, v56, v57
	v_sub_f32_e32 v60, v60, v174
	v_exp_f32_e32 v60, v60
	v_add_f32_e32 v213, v59, v213
	v_sub_f32_e32 v61, v61, v174
	v_exp_f32_e32 v61, v61
	v_add_f32_e32 v213, v60, v213
	v_cvt_pk_bf16_f32 v85, v58, v59
	v_sub_f32_e32 v62, v62, v174
	v_exp_f32_e32 v62, v62
	v_add_f32_e32 v213, v61, v213
	v_sub_f32_e32 v63, v63, v174
	v_exp_f32_e32 v63, v63
	v_add_f32_e32 v213, v62, v213
	v_cvt_pk_bf16_f32 v86, v60, v61
	v_add_f32_e32 v213, v63, v213
	v_cvt_pk_bf16_f32 v87, v62, v63
	v_fmac_f32_e32 v213, v169, v0
	v_mov_b32_e32 v169, v213
	s_nop 0
	s_waitcnt lgkmcnt(1)
	v_mfma_f32_32x32x16_bf16 v[32:47], v[228:231], v[84:87], v[32:47]
	s_waitcnt lgkmcnt(0)
	v_mfma_f32_32x32x16_bf16 v[16:31], v[232:235], v[84:87], v[16:31]
	s_branch .LBB0_296

.LBB0_307:
	s_and_b64 vcc, exec, s[4:5]
	s_cbranch_vccz .Lnsw1_edgeback
	v_mad_u32_u24 v0, v117, s37, v14
	v_lshl_add_u32 v215, v159, 1, v15
	ds_read_b128 v[220:223], v0
	ds_read_b128 v[236:239], v0 offset:4608
	ds_read_b128 v[224:227], v0 offset:32
	ds_read_b128 v[240:243], v0 offset:4640
	ds_read_b128 v[228:231], v0 offset:64
	ds_read_b128 v[244:247], v0 offset:4672
	ds_read_b128 v[232:235], v0 offset:96
	ds_read_b128 v[248:251], v0 offset:4704
	v_add_u32_e32 v214, 0x3000, v215
	v_add_u32_e32 v215, 0x2000, v215
	ds_read2_b64 v[64:67], v215 offset0:128 offset1:130
	ds_read2_b64 v[68:71], v214 offset0:192 offset1:194
	ds_read2_b64 v[72:75], v215 offset0:132 offset1:134
	ds_read2_b64 v[76:79], v214 offset0:196 offset1:198
	s_waitcnt lgkmcnt(11)
	v_mfma_f32_32x32x16_bf16 v[80:95], v[220:223], v[96:99], 0
	s_waitcnt lgkmcnt(10)
	v_mfma_f32_32x32x16_bf16 v[48:63], v[236:239], v[96:99], 0
	s_waitcnt lgkmcnt(9)
	v_mfma_f32_32x32x16_bf16 v[80:95], v[224:227], v[100:103], v[80:95]
	s_waitcnt lgkmcnt(8)
	v_mfma_f32_32x32x16_bf16 v[48:63], v[240:243], v[100:103], v[48:63]
	s_waitcnt lgkmcnt(7)
	v_mfma_f32_32x32x16_bf16 v[80:95], v[228:231], v[104:107], v[80:95]
	s_waitcnt lgkmcnt(6)
	v_mfma_f32_32x32x16_bf16 v[48:63], v[244:247], v[104:107], v[48:63]
	s_waitcnt lgkmcnt(5)
	v_mfma_f32_32x32x16_bf16 v[80:95], v[232:235], v[108:111], v[80:95]
	s_waitcnt lgkmcnt(4)
	v_mfma_f32_32x32x16_bf16 v[48:63], v[248:251], v[108:111], v[48:63]
	ds_read2_b64 v[220:223], v215 offset0:136 offset1:138
	ds_read2_b64 v[224:227], v214 offset0:200 offset1:202
	ds_read2_b64 v[228:231], v215 offset0:140 offset1:142
	ds_read2_b64 v[232:235], v214 offset0:204 offset1:206
	s_nop 7
	v_max3_f32 v0, v80, v81, v82
	v_max3_f32 v216, v88, v89, v90
	v_max3_f32 v0, v0, v83, v84
	v_max3_f32 v216, v216, v91, v92
	v_max3_f32 v0, v0, v85, v86
	v_max3_f32 v216, v216, v93, v94
	v_max3_f32 v0, v0, v87, v95
	v_max_f32_e32 v0, v0, v216
	v_mov_b32_e32 v216, v0
	s_nop 1
	v_permlane32_swap_b32_e32 v0, v216
	v_max3_f32 v173, v168, v0, v216
	v_sub_f32_e32 v0, v168, v173
	v_exp_f32_e32 v0, v0
	v_cmp_eq_f32_e32 vcc, v173, v168
	s_cmp_eq_u64 vcc, exec
	s_cbranch_scc1 .Lnsw1_keep0
	v_pk_mul_f32 v[46:47], v[46:47], v[0:1] op_sel_hi:[1,0]
	v_pk_mul_f32 v[44:45], v[44:45], v[0:1] op_sel_hi:[1,0]
	v_pk_mul_f32 v[42:43], v[42:43], v[0:1] op_sel_hi:[1,0]
	v_pk_mul_f32 v[40:41], v[40:41], v[0:1] op_sel_hi:[1,0]
	v_pk_mul_f32 v[38:39], v[38:39], v[0:1] op_sel_hi:[1,0]
	v_pk_mul_f32 v[36:37], v[36:37], v[0:1] op_sel_hi:[1,0]
	v_pk_mul_f32 v[34:35], v[34:35], v[0:1] op_sel_hi:[1,0]
	v_pk_mul_f32 v[32:33], v[32:33], v[0:1] op_sel_hi:[1,0]
	v_pk_mul_f32 v[30:31], v[30:31], v[0:1] op_sel_hi:[1,0]
	v_pk_mul_f32 v[28:29], v[28:29], v[0:1] op_sel_hi:[1,0]
	v_pk_mul_f32 v[26:27], v[26:27], v[0:1] op_sel_hi:[1,0]
	v_pk_mul_f32 v[24:25], v[24:25], v[0:1] op_sel_hi:[1,0]
	v_pk_mul_f32 v[22:23], v[22:23], v[0:1] op_sel_hi:[1,0]
	v_pk_mul_f32 v[20:21], v[20:21], v[0:1] op_sel_hi:[1,0]
	v_pk_mul_f32 v[18:19], v[18:19], v[0:1] op_sel_hi:[1,0]
	v_pk_mul_f32 v[16:17], v[16:17], v[0:1] op_sel_hi:[1,0]
.Lnsw1_keep0:
	v_mov_b32_e32 v168, v173
	v_mov_b32_e32 v174, v173
	v_sub_f32_e32 v80, v80, v174
	v_exp_f32_e32 v80, v80
	v_sub_f32_e32 v81, v81, v174
	v_exp_f32_e32 v81, v81
	v_add_f32_e32 v213, 0, v80
	v_sub_f32_e32 v82, v82, v174
	v_exp_f32_e32 v82, v82
	v_add_f32_e32 v213, v81, v213
	v_sub_f32_e32 v83, v83, v174
	v_exp_f32_e32 v83, v83
	v_add_f32_e32 v213, v82, v213
	v_cvt_pk_bf16_f32 v176, v80, v81
	v_sub_f32_e32 v84, v84, v174
	v_exp_f32_e32 v84, v84
	v_add_f32_e32 v213, v83, v213
	v_sub_f32_e32 v85, v85, v174
	v_exp_f32_e32 v85, v85
	v_add_f32_e32 v213, v84, v213
	v_cvt_pk_bf16_f32 v177, v82, v83
	v_sub_f32_e32 v86, v86, v174
	v_exp_f32_e32 v86, v86
	v_add_f32_e32 v213, v85, v213
	v_sub_f32_e32 v87, v87, v174
	v_exp_f32_e32 v87, v87
	v_add_f32_e32 v213, v86, v213
	v_cvt_pk_bf16_f32 v178, v84, v85
	v_sub_f32_e32 v88, v88, v174
	v_exp_f32_e32 v88, v88
	v_add_f32_e32 v213, v87, v213
	v_sub_f32_e32 v89, v89, v174
	v_exp_f32_e32 v89, v89
	v_add_f32_e32 v213, v88, v213
	v_cvt_pk_bf16_f32 v179, v86, v87
	v_sub_f32_e32 v90, v90, v174
	v_exp_f32_e32 v90, v90
	v_add_f32_e32 v213, v89, v213
	s_waitcnt lgkmcnt(7)
	v_mfma_f32_32x32x16_bf16 v[32:47], v[64:67], v[176:179], v[32:47]
	s_waitcnt lgkmcnt(6)
	v_mfma_f32_32x32x16_bf16 v[16:31], v[68:71], v[176:179], v[16:31]
	v_sub_f32_e32 v91, v91, v174
	v_exp_f32_e32 v91, v91
	v_add_f32_e32 v213, v90, v213
	v_cvt_pk_bf16_f32 v180, v88, v89
	v_sub_f32_e32 v92, v92, v174
	v_exp_f32_e32 v92, v92
	v_add_f32_e32 v213, v91, v213
	v_sub_f32_e32 v93, v93, v174
	v_exp_f32_e32 v93, v93
	v_add_f32_e32 v213, v92, v213
	v_cvt_pk_bf16_f32 v181, v90, v91
	v_sub_f32_e32 v94, v94, v174
	v_exp_f32_e32 v94, v94
	v_add_f32_e32 v213, v93, v213
	v_sub_f32_e32 v95, v95, v174
	v_exp_f32_e32 v95, v95
	v_add_f32_e32 v213, v94, v213
	v_cvt_pk_bf16_f32 v182, v92, v93
	v_add_f32_e32 v213, v95, v213
	v_cvt_pk_bf16_f32 v183, v94, v95
	v_fmac_f32_e32 v213, v169, v0
	v_mov_b32_e32 v169, v213
	s_nop 0
	s_waitcnt lgkmcnt(5)
	v_mfma_f32_32x32x16_bf16 v[32:47], v[72:75], v[180:183], v[32:47]
	s_waitcnt lgkmcnt(4)
	v_mfma_f32_32x32x16_bf16 v[16:31], v[76:79], v[180:183], v[16:31]
	v_max3_f32 v0, v48, v49, v50
	v_max3_f32 v216, v56, v57, v58
	v_max3_f32 v0, v0, v51, v52
	v_max3_f32 v216, v216, v59, v60
	v_max3_f32 v0, v0, v53, v54
	v_max3_f32 v216, v216, v61, v62
	v_max3_f32 v0, v0, v55, v63
	v_max_f32_e32 v0, v0, v216
	v_mov_b32_e32 v216, v0
	s_nop 1
	v_permlane32_swap_b32_e32 v0, v216
	v_max3_f32 v173, v168, v0, v216
	v_sub_f32_e32 v0, v168, v173
	v_exp_f32_e32 v0, v0
	v_cmp_eq_f32_e32 vcc, v173, v168
	s_cmp_eq_u64 vcc, exec
	s_cbranch_scc1 .Lnsw1_keep1
	v_pk_mul_f32 v[46:47], v[46:47], v[0:1] op_sel_hi:[1,0]
	v_pk_mul_f32 v[44:45], v[44:45], v[0:1] op_sel_hi:[1,0]
	v_pk_mul_f32 v[42:43], v[42:43], v[0:1] op_sel_hi:[1,0]
	v_pk_mul_f32 v[40:41], v[40:41], v[0:1] op_sel_hi:[1,0]
	v_pk_mul_f32 v[38:39], v[38:39], v[0:1] op_sel_hi:[1,0]
	v_pk_mul_f32 v[36:37], v[36:37], v[0:1] op_sel_hi:[1,0]
	v_pk_mul_f32 v[34:35], v[34:35], v[0:1] op_sel_hi:[1,0]
	v_pk_mul_f32 v[32:33], v[32:33], v[0:1] op_sel_hi:[1,0]
	v_pk_mul_f32 v[30:31], v[30:31], v[0:1] op_sel_hi:[1,0]
	v_pk_mul_f32 v[28:29], v[28:29], v[0:1] op_sel_hi:[1,0]
	v_pk_mul_f32 v[26:27], v[26:27], v[0:1] op_sel_hi:[1,0]
	v_pk_mul_f32 v[24:25], v[24:25], v[0:1] op_sel_hi:[1,0]
	v_pk_mul_f32 v[22:23], v[22:23], v[0:1] op_sel_hi:[1,0]
	v_pk_mul_f32 v[20:21], v[20:21], v[0:1] op_sel_hi:[1,0]
	v_pk_mul_f32 v[18:19], v[18:19], v[0:1] op_sel_hi:[1,0]
	v_pk_mul_f32 v[16:17], v[16:17], v[0:1] op_sel_hi:[1,0]
.Lnsw1_keep1:
	v_mov_b32_e32 v168, v173
	v_mov_b32_e32 v174, v173
	v_sub_f32_e32 v48, v48, v174
	v_exp_f32_e32 v48, v48
	v_sub_f32_e32 v49, v49, v174
	v_exp_f32_e32 v49, v49
	v_add_f32_e32 v213, 0, v48
	v_sub_f32_e32 v50, v50, v174
	v_exp_f32_e32 v50, v50
	v_add_f32_e32 v213, v49, v213
	v_sub_f32_e32 v51, v51, v174
	v_exp_f32_e32 v51, v51
	v_add_f32_e32 v213, v50, v213
	v_cvt_pk_bf16_f32 v80, v48, v49
	v_sub_f32_e32 v52, v52, v174
	v_exp_f32_e32 v52, v52
	v_add_f32_e32 v213, v51, v213
	v_sub_f32_e32 v53, v53, v174
	v_exp_f32_e32 v53, v53
	v_add_f32_e32 v213, v52, v213
	v_cvt_pk_bf16_f32 v81, v50, v51
	v_sub_f32_e32 v54, v54, v174
	v_exp_f32_e32 v54, v54
	v_add_f32_e32 v213, v53, v213
	v_sub_f32_e32 v55, v55, v174
	v_exp_f32_e32 v55, v55
	v_add_f32_e32 v213, v54, v213
	v_cvt_pk_bf16_f32 v82, v52, v53
	v_sub_f32_e32 v56, v56, v174
	v_exp_f32_e32 v56, v56
	v_add_f32_e32 v213, v55, v213
	v_sub_f32_e32 v57, v57, v174
	v_exp_f32_e32 v57, v57
	v_add_f32_e32 v213, v56, v213
	v_cvt_pk_bf16_f32 v83, v54, v55
	v_sub_f32_e32 v58, v58, v174
	v_exp_f32_e32 v58, v58
	v_add_f32_e32 v213, v57, v213
	s_waitcnt lgkmcnt(3)
	v_mfma_f32_32x32x16_bf16 v[32:47], v[220:223], v[80:83], v[32:47]
	s_waitcnt lgkmcnt(2)
	v_mfma_f32_32x32x16_bf16 v[16:31], v[224:227], v[80:83], v[16:31]
	v_sub_f32_e32 v59, v59, v174
	v_exp_f32_e32 v59, v59
	v_add_f32_e32 v213, v58, v213
	v_cvt_pk_bf16_f32 v84, v56, v57
	v_sub_f32_e32 v60, v60, v174
	v_exp_f32_e32 v60, v60
	v_add_f32_e32 v213, v59, v213
	v_sub_f32_e32 v61, v61, v174
	v_exp_f32_e32 v61, v61
	v_add_f32_e32 v213, v60, v213
	v_cvt_pk_bf16_f32 v85, v58, v59
	v_sub_f32_e32 v62, v62, v174
	v_exp_f32_e32 v62, v62
	v_add_f32_e32 v213, v61, v213
	v_sub_f32_e32 v63, v63, v174
	v_exp_f32_e32 v63, v63
	v_add_f32_e32 v213, v62, v213
	v_cvt_pk_bf16_f32 v86, v60, v61
	v_add_f32_e32 v213, v63, v213
	v_cvt_pk_bf16_f32 v87, v62, v63
	v_fmac_f32_e32 v213, v169, v0
	v_mov_b32_e32 v169, v213
	s_nop 0
	s_waitcnt lgkmcnt(1)
	v_mfma_f32_32x32x16_bf16 v[32:47], v[228:231], v[84:87], v[32:47]
	s_waitcnt lgkmcnt(0)
	v_mfma_f32_32x32x16_bf16 v[16:31], v[232:235], v[84:87], v[16:31]
	s_branch .LBB0_314
